# speedup vs baseline: 1.0213x; 1.0040x over previous
; template <int N, int K, int EPI>
; __device__ __forceinline__ void gemm_phase(const bf16* __restrict__ A, const bf16* __restrict__ Bt, float* __restrict__ outf, bf16* __restrict__ outb,
;                            const float* __restrict__ ropec, const int W) {
;     ...
;       char* obase = (char*)(outb + (size_t)brow * N + bcol);
; #pragma unroll
;       for (int ai = 0; ai < 2; ++ai)
; #pragma unroll
;         for (int bj = 0; bj < 2; ++bj)
; #pragma unroll
;           for (int m = 0; m < 4; ++m) {
;             const unsigned lrow = ai * HALF + wr * 64 + m * 16 + efr;
;             const unsigned lcol = bj * HALF + wcb + efq * 8;
;             const f32x4 v0 = acc[ai][bj][m][0], v1 = acc[ai][bj][m][1];
;             if (EPI == EPI_RES) {
;               u32x4* d = (u32x4*)(obase + (size_t)((lrow * N + lcol) * 2u));
;               const u32x4 t = *d;
;               const f32x4 r0 = bf4_to_f32(u32x2{t[0], t[1]}) + v0, r1 = bf4_to_f32(u32x2{t[2], t[3]}) + v1;
;               u32x4 w = {cvtpk(r0[0], r0[1]), cvtpk(r0[2], r0[3]), cvtpk(r1[0], r1[1]), cvtpk(r1[2], r1[3])};
;               *d = w;
;             } else {
;               const float a0 = fmaxf(v0[0], 0.f), a1 = fmaxf(v0[1], 0.f), a2 = fmaxf(v0[2], 0.f), a3 = fmaxf(v0[3], 0.f);
;               const float b0 = fmaxf(v1[0], 0.f), b1 = fmaxf(v1[1], 0.f), b2 = fmaxf(v1[2], 0.f), b3 = fmaxf(v1[3], 0.f);
;               u32x4 w = {cvtpk(a0 * a0, a1 * a1), cvtpk(a2 * a2, a3 * a3), cvtpk(b0 * b0, b1 * b1), cvtpk(b2 * b2, b3 * b3)};
;               *(u32x4*)(obase + (size_t)((lrow * N + lcol) * 2u)) = w;
;             }
.LBB0_187:
	v_max_f32_e32 v120, v120, v120
	v_max_f32_e32 v158, 0, v120
	v_max_f32_e32 v120, v121, v121
	v_max_f32_e32 v124, v124, v124
	v_max_f32_e32 v125, v125, v125
	v_max_f32_e32 v159, 0, v120
	v_max_f32_e32 v120, v122, v122
	v_max_f32_e32 v124, 0, v124
	v_max_f32_e32 v125, 0, v125
	v_max_f32_e32 v126, v126, v126
	v_max_f32_e32 v127, v127, v127
	v_max_f32_e32 v160, 0, v120
	v_max_f32_e32 v120, v123, v123
	v_max_f32_e32 v126, 0, v126
	v_max_f32_e32 v127, 0, v127
	v_max_f32_e32 v123, 0, v120
	v_mul_f32_e32 v120, v124, v124
	v_mul_f32_e32 v121, v125, v125
	v_mbcnt_lo_u32_b32 v132, -1, 0
	v_mbcnt_hi_u32_b32 v132, -1, v132
	v_cvt_pk_bf16_f32 v120, v120, v121
	v_mul_f32_e32 v121, v126, v126
	v_mul_f32_e32 v122, v127, v127
	v_cvt_pk_bf16_f32 v121, v121, v122
	v_mul_f32_e32 v122, v158, v158
	v_mul_f32_e32 v124, v159, v159
	v_cvt_pk_bf16_f32 v122, v122, v124
	v_mul_f32_e32 v124, v160, v160
	v_mul_f32_e32 v123, v123, v123
	s_lshl_b64 s[6:7], s[96:97], 13
	v_cvt_pk_bf16_f32 v123, v124, v123
	v_lshlrev_b32_e32 v124, 12, v132
	s_add_u32 s80, s36, s6
	v_lshrrev_b32_e32 v133, 1, v132
	v_and_b32_e32 v124, 0xf000, v124
	s_addc_u32 s81, s37, s7
	s_lshl_b64 s[6:7], s[94:95], 1
	v_and_or_b32 v133, v133, 24, s4
	v_or_b32_e32 v124, s5, v124
	s_add_u32 s80, s80, s6
	v_or_b32_e32 v125, v124, v133
	s_addc_u32 s81, s81, s7
	v_lshlrev_b32_e32 v125, 1, v125
	v_max_f32_e32 v112, v112, v112
	global_store_dwordx4 v125, v[120:123], s[80:81] sc1
	v_max_f32_e32 v116, v116, v116
	v_max_f32_e32 v117, v117, v117
	v_max_f32_e32 v120, 0, v112
	v_max_f32_e32 v112, v113, v113
	v_max_f32_e32 v121, 0, v112
	v_max_f32_e32 v112, v114, v114
	v_max_f32_e32 v116, 0, v116
	v_max_f32_e32 v117, 0, v117
	v_max_f32_e32 v118, v118, v118
	v_max_f32_e32 v119, v119, v119
	v_max_f32_e32 v122, 0, v112
	v_max_f32_e32 v112, v115, v115
	v_max_f32_e32 v118, 0, v118
	v_max_f32_e32 v119, 0, v119
	v_max_f32_e32 v115, 0, v112
	v_mul_f32_e32 v112, v116, v116
	v_mul_f32_e32 v113, v117, v117
	v_cvt_pk_bf16_f32 v112, v112, v113
	v_mul_f32_e32 v113, v118, v118
	v_mul_f32_e32 v114, v119, v119
	v_cvt_pk_bf16_f32 v113, v113, v114
	v_mul_f32_e32 v114, v120, v120
	v_mul_f32_e32 v116, v121, v121
	v_cvt_pk_bf16_f32 v114, v114, v116
	v_mul_f32_e32 v116, v122, v122
	v_mul_f32_e32 v115, v115, v115
	v_cvt_pk_bf16_f32 v115, v116, v115
	v_or_b32_e32 v116, 0x10000, v124
	v_or_b32_e32 v117, v116, v133
	v_lshlrev_b32_e32 v117, 1, v117
	v_max_f32_e32 v104, v104, v104
	global_store_dwordx4 v117, v[112:115], s[80:81] sc1
	v_max_f32_e32 v108, v108, v108
	v_max_f32_e32 v109, v109, v109
	v_max_f32_e32 v112, 0, v104
	v_max_f32_e32 v104, v105, v105
	v_max_f32_e32 v113, 0, v104
	v_max_f32_e32 v104, v106, v106
	v_max_f32_e32 v108, 0, v108
	v_max_f32_e32 v109, 0, v109
	v_max_f32_e32 v110, v110, v110
	v_max_f32_e32 v111, v111, v111
	v_max_f32_e32 v114, 0, v104
	v_max_f32_e32 v104, v107, v107
	v_max_f32_e32 v110, 0, v110
	v_max_f32_e32 v111, 0, v111
	v_max_f32_e32 v107, 0, v104
	v_mul_f32_e32 v104, v108, v108
	v_mul_f32_e32 v105, v109, v109
	v_cvt_pk_bf16_f32 v104, v104, v105
	v_mul_f32_e32 v105, v110, v110
	v_mul_f32_e32 v106, v111, v111
	v_cvt_pk_bf16_f32 v105, v105, v106
	v_mul_f32_e32 v106, v112, v112
	v_mul_f32_e32 v108, v113, v113
	v_cvt_pk_bf16_f32 v106, v106, v108
	v_mul_f32_e32 v108, v114, v114
	v_mul_f32_e32 v107, v107, v107
	v_cvt_pk_bf16_f32 v107, v108, v107
	v_or_b32_e32 v108, 0x20000, v124
	v_or_b32_e32 v109, v108, v133
	v_lshlrev_b32_e32 v109, 1, v109
	v_max_f32_e32 v96, v96, v96
	global_store_dwordx4 v109, v[104:107], s[80:81] sc1
	v_max_f32_e32 v100, v100, v100
	v_max_f32_e32 v101, v101, v101
	v_max_f32_e32 v104, 0, v96
	v_max_f32_e32 v96, v97, v97
	v_max_f32_e32 v105, 0, v96
	v_max_f32_e32 v96, v98, v98
	v_max_f32_e32 v100, 0, v100
	v_max_f32_e32 v101, 0, v101
	v_max_f32_e32 v102, v102, v102
	v_max_f32_e32 v103, v103, v103
	v_max_f32_e32 v106, 0, v96
	v_max_f32_e32 v96, v99, v99
	v_max_f32_e32 v102, 0, v102
	v_max_f32_e32 v103, 0, v103
	v_max_f32_e32 v99, 0, v96
	v_mul_f32_e32 v96, v100, v100
	v_mul_f32_e32 v97, v101, v101
	v_cvt_pk_bf16_f32 v96, v96, v97
	v_mul_f32_e32 v97, v102, v102
	v_mul_f32_e32 v98, v103, v103
	v_cvt_pk_bf16_f32 v97, v97, v98
	v_mul_f32_e32 v98, v104, v104
	v_mul_f32_e32 v100, v105, v105
	v_cvt_pk_bf16_f32 v98, v98, v100
	v_mul_f32_e32 v100, v106, v106
	v_mul_f32_e32 v99, v99, v99
	v_cvt_pk_bf16_f32 v99, v100, v99
	v_or_b32_e32 v100, 0x30000, v124
	v_or_b32_e32 v101, v100, v133
	v_lshlrev_b32_e32 v101, 1, v101
	v_max_f32_e32 v88, v88, v88
	global_store_dwordx4 v101, v[96:99], s[80:81] sc1
	v_max_f32_e32 v92, v92, v92
	v_max_f32_e32 v93, v93, v93
	v_max_f32_e32 v97, 0, v88
	v_max_f32_e32 v88, v89, v89
	v_max_f32_e32 v98, 0, v88
	v_max_f32_e32 v88, v90, v90
	v_max_f32_e32 v92, 0, v92
	v_max_f32_e32 v93, 0, v93
	v_max_f32_e32 v94, v94, v94
	v_max_f32_e32 v95, v95, v95
	v_max_f32_e32 v99, 0, v88
	v_max_f32_e32 v88, v91, v91
	v_max_f32_e32 v94, 0, v94
	v_max_f32_e32 v95, 0, v95
	v_max_f32_e32 v91, 0, v88
	v_mul_f32_e32 v88, v92, v92
	v_mul_f32_e32 v89, v93, v93
	v_cvt_pk_bf16_f32 v88, v88, v89
	v_mul_f32_e32 v89, v94, v94
	v_mul_f32_e32 v90, v95, v95
	v_cvt_pk_bf16_f32 v89, v89, v90
	v_mul_f32_e32 v90, v97, v97
	v_mul_f32_e32 v92, v98, v98
	v_or_b32_e32 v96, 0x80, v133
	v_cvt_pk_bf16_f32 v90, v90, v92
	v_mul_f32_e32 v92, v99, v99
	v_mul_f32_e32 v91, v91, v91
	v_cvt_pk_bf16_f32 v91, v92, v91
	v_or_b32_e32 v92, v96, v124
	v_lshlrev_b32_e32 v92, 1, v92
	v_max_f32_e32 v80, v80, v80
	global_store_dwordx4 v92, v[88:91], s[80:81] sc1
	v_max_f32_e32 v84, v84, v84
	v_max_f32_e32 v85, v85, v85
	v_max_f32_e32 v88, 0, v80
	v_max_f32_e32 v80, v81, v81
	v_max_f32_e32 v89, 0, v80
	v_max_f32_e32 v80, v82, v82
; template <int N, int K, int EPI>
; __device__ __forceinline__ void gemm_phase(const bf16* __restrict__ A, const bf16* __restrict__ Bt, float* __restrict__ outf, bf16* __restrict__ outb,
;                            const float* __restrict__ ropec, const int W) {
;     ...
;       char* obase = (char*)(outb + (size_t)brow * N + bcol);
; #pragma unroll
;       for (int ai = 0; ai < 2; ++ai)
; #pragma unroll
;         for (int bj = 0; bj < 2; ++bj)
; #pragma unroll
;           for (int m = 0; m < 4; ++m) {
;             const unsigned lrow = ai * HALF + wr * 64 + m * 16 + efr;
;             const unsigned lcol = bj * HALF + wcb + efq * 8;
;             const f32x4 v0 = acc[ai][bj][m][0], v1 = acc[ai][bj][m][1];
;             if (EPI == EPI_RES) {
;               u32x4* d = (u32x4*)(obase + (size_t)((lrow * N + lcol) * 2u));
;               const u32x4 t = *d;
;               const f32x4 r0 = bf4_to_f32(u32x2{t[0], t[1]}) + v0, r1 = bf4_to_f32(u32x2{t[2], t[3]}) + v1;
;               u32x4 w = {cvtpk(r0[0], r0[1]), cvtpk(r0[2], r0[3]), cvtpk(r1[0], r1[1]), cvtpk(r1[2], r1[3])};
;               *d = w;
;             } else {
;               const float a0 = fmaxf(v0[0], 0.f), a1 = fmaxf(v0[1], 0.f), a2 = fmaxf(v0[2], 0.f), a3 = fmaxf(v0[3], 0.f);
;               const float b0 = fmaxf(v1[0], 0.f), b1 = fmaxf(v1[1], 0.f), b2 = fmaxf(v1[2], 0.f), b3 = fmaxf(v1[3], 0.f);
;               u32x4 w = {cvtpk(a0 * a0, a1 * a1), cvtpk(a2 * a2, a3 * a3), cvtpk(b0 * b0, b1 * b1), cvtpk(b2 * b2, b3 * b3)};
;               *(u32x4*)(obase + (size_t)((lrow * N + lcol) * 2u)) = w;
;             }
	v_max_f32_e32 v84, 0, v84
	v_max_f32_e32 v85, 0, v85
	v_max_f32_e32 v86, v86, v86
	v_max_f32_e32 v87, v87, v87
	v_max_f32_e32 v90, 0, v80
	v_max_f32_e32 v80, v83, v83
	v_max_f32_e32 v86, 0, v86
	v_max_f32_e32 v87, 0, v87
	v_max_f32_e32 v83, 0, v80
	v_mul_f32_e32 v80, v84, v84
	v_mul_f32_e32 v81, v85, v85
	v_cvt_pk_bf16_f32 v80, v80, v81
	v_mul_f32_e32 v81, v86, v86
	v_mul_f32_e32 v82, v87, v87
	v_cvt_pk_bf16_f32 v81, v81, v82
	v_mul_f32_e32 v82, v88, v88
	v_mul_f32_e32 v84, v89, v89
	v_cvt_pk_bf16_f32 v82, v82, v84
	v_mul_f32_e32 v84, v90, v90
	v_mul_f32_e32 v83, v83, v83
	v_cvt_pk_bf16_f32 v83, v84, v83
	v_or_b32_e32 v84, v116, v96
	v_lshlrev_b32_e32 v84, 1, v84
	v_max_f32_e32 v72, v72, v72
	global_store_dwordx4 v84, v[80:83], s[80:81] sc1
	v_max_f32_e32 v76, v76, v76
	v_max_f32_e32 v77, v77, v77
	v_max_f32_e32 v80, 0, v72
	v_max_f32_e32 v72, v73, v73
	v_max_f32_e32 v81, 0, v72
	v_max_f32_e32 v72, v74, v74
	v_max_f32_e32 v76, 0, v76
	v_max_f32_e32 v77, 0, v77
	v_max_f32_e32 v78, v78, v78
	v_max_f32_e32 v79, v79, v79
	v_max_f32_e32 v82, 0, v72
	v_max_f32_e32 v72, v75, v75
	v_max_f32_e32 v78, 0, v78
	v_max_f32_e32 v79, 0, v79
	v_max_f32_e32 v75, 0, v72
	v_mul_f32_e32 v72, v76, v76
	v_mul_f32_e32 v73, v77, v77
	v_cvt_pk_bf16_f32 v72, v72, v73
	v_mul_f32_e32 v73, v78, v78
	v_mul_f32_e32 v74, v79, v79
	v_cvt_pk_bf16_f32 v73, v73, v74
	v_mul_f32_e32 v74, v80, v80
	v_mul_f32_e32 v76, v81, v81
	v_cvt_pk_bf16_f32 v74, v74, v76
	v_mul_f32_e32 v76, v82, v82
	v_mul_f32_e32 v75, v75, v75
	v_cvt_pk_bf16_f32 v75, v76, v75
	v_or_b32_e32 v76, v108, v96
	v_lshlrev_b32_e32 v76, 1, v76
	v_max_f32_e32 v64, v64, v64
	global_store_dwordx4 v76, v[72:75], s[80:81] sc1
	v_max_f32_e32 v68, v68, v68
	v_max_f32_e32 v69, v69, v69
	v_max_f32_e32 v72, 0, v64
	v_max_f32_e32 v64, v65, v65
	v_max_f32_e32 v73, 0, v64
	v_max_f32_e32 v64, v66, v66
	v_max_f32_e32 v68, 0, v68
	v_max_f32_e32 v69, 0, v69
	v_max_f32_e32 v70, v70, v70
	v_max_f32_e32 v71, v71, v71
	v_max_f32_e32 v74, 0, v64
	v_max_f32_e32 v64, v67, v67
	v_max_f32_e32 v70, 0, v70
	v_max_f32_e32 v71, 0, v71
	v_max_f32_e32 v67, 0, v64
	v_mul_f32_e32 v64, v68, v68
	v_mul_f32_e32 v65, v69, v69
	v_cvt_pk_bf16_f32 v64, v64, v65
	v_mul_f32_e32 v65, v70, v70
	v_mul_f32_e32 v66, v71, v71
	v_cvt_pk_bf16_f32 v65, v65, v66
	v_mul_f32_e32 v66, v72, v72
	v_mul_f32_e32 v68, v73, v73
	v_cvt_pk_bf16_f32 v66, v66, v68
	v_mul_f32_e32 v68, v74, v74
	v_mul_f32_e32 v67, v67, v67
	v_cvt_pk_bf16_f32 v67, v68, v67
	v_or_b32_e32 v68, v100, v96
	v_lshlrev_b32_e32 v68, 1, v68
	v_max_f32_e32 v56, v56, v56
	global_store_dwordx4 v68, v[64:67], s[80:81] sc1
	v_max_f32_e32 v60, v60, v60
	v_max_f32_e32 v61, v61, v61
	v_max_f32_e32 v64, 0, v56
	v_max_f32_e32 v56, v57, v57
	v_max_f32_e32 v65, 0, v56
	v_max_f32_e32 v56, v58, v58
	v_max_f32_e32 v60, 0, v60
	v_max_f32_e32 v61, 0, v61
	v_max_f32_e32 v62, v62, v62
	v_max_f32_e32 v63, v63, v63
	v_max_f32_e32 v66, 0, v56
	v_max_f32_e32 v56, v59, v59
	v_max_f32_e32 v62, 0, v62
	v_max_f32_e32 v63, 0, v63
	v_max_f32_e32 v59, 0, v56
	v_mul_f32_e32 v56, v60, v60
	v_mul_f32_e32 v57, v61, v61
	v_cvt_pk_bf16_f32 v56, v56, v57
	v_mul_f32_e32 v57, v62, v62
	v_mul_f32_e32 v58, v63, v63
	v_cvt_pk_bf16_f32 v57, v57, v58
	v_mul_f32_e32 v58, v64, v64
	v_mul_f32_e32 v60, v65, v65
	v_cvt_pk_bf16_f32 v58, v58, v60
	v_mul_f32_e32 v60, v66, v66
	v_mul_f32_e32 v59, v59, v59
	v_cvt_pk_bf16_f32 v59, v60, v59
	v_add_u32_e32 v60, 0x80000, v124
	v_or_b32_e32 v61, v60, v133
	v_lshlrev_b32_e32 v61, 1, v61
	v_max_f32_e32 v48, v48, v48
	global_store_dwordx4 v61, v[56:59], s[80:81] sc1
	v_max_f32_e32 v52, v52, v52
	v_max_f32_e32 v53, v53, v53
	v_max_f32_e32 v56, 0, v48
	v_max_f32_e32 v48, v49, v49
	v_max_f32_e32 v57, 0, v48
	v_max_f32_e32 v48, v50, v50
	v_max_f32_e32 v52, 0, v52
	v_max_f32_e32 v53, 0, v53
	v_max_f32_e32 v54, v54, v54
	v_max_f32_e32 v55, v55, v55
	v_max_f32_e32 v58, 0, v48
	v_max_f32_e32 v48, v51, v51
	v_max_f32_e32 v54, 0, v54
	v_max_f32_e32 v55, 0, v55
	v_max_f32_e32 v51, 0, v48
	v_mul_f32_e32 v48, v52, v52
	v_mul_f32_e32 v49, v53, v53
	v_cvt_pk_bf16_f32 v48, v48, v49
	v_mul_f32_e32 v49, v54, v54
	v_mul_f32_e32 v50, v55, v55
	v_cvt_pk_bf16_f32 v49, v49, v50
	v_mul_f32_e32 v50, v56, v56
	v_mul_f32_e32 v52, v57, v57
	v_cvt_pk_bf16_f32 v50, v50, v52
	v_mul_f32_e32 v52, v58, v58
	v_mul_f32_e32 v51, v51, v51
	v_cvt_pk_bf16_f32 v51, v52, v51
	v_add_u32_e32 v52, 0x90000, v124
	v_or_b32_e32 v53, v52, v133
	v_lshlrev_b32_e32 v53, 1, v53
	v_max_f32_e32 v40, v40, v40
	global_store_dwordx4 v53, v[48:51], s[80:81] sc1
	v_max_f32_e32 v44, v44, v44
	v_max_f32_e32 v45, v45, v45
	v_max_f32_e32 v48, 0, v40
	v_max_f32_e32 v40, v41, v41
	v_max_f32_e32 v49, 0, v40
	v_max_f32_e32 v40, v42, v42
	v_max_f32_e32 v44, 0, v44
	v_max_f32_e32 v45, 0, v45
	v_max_f32_e32 v46, v46, v46
	v_max_f32_e32 v47, v47, v47
	v_max_f32_e32 v50, 0, v40
	v_max_f32_e32 v40, v43, v43
	v_max_f32_e32 v46, 0, v46
	v_max_f32_e32 v47, 0, v47
	v_max_f32_e32 v43, 0, v40
	v_mul_f32_e32 v40, v44, v44
	v_mul_f32_e32 v41, v45, v45
	v_cvt_pk_bf16_f32 v40, v40, v41
	v_mul_f32_e32 v41, v46, v46
; template <int N, int K, int EPI>
; __device__ __forceinline__ void gemm_phase(const bf16* __restrict__ A, const bf16* __restrict__ Bt, float* __restrict__ outf, bf16* __restrict__ outb,
;                            const float* __restrict__ ropec, const int W) {
;     ...
;       char* obase = (char*)(outb + (size_t)brow * N + bcol);
; #pragma unroll
;       for (int ai = 0; ai < 2; ++ai)
; #pragma unroll
;         for (int bj = 0; bj < 2; ++bj)
; #pragma unroll
;           for (int m = 0; m < 4; ++m) {
;             const unsigned lrow = ai * HALF + wr * 64 + m * 16 + efr;
;             const unsigned lcol = bj * HALF + wcb + efq * 8;
;             const f32x4 v0 = acc[ai][bj][m][0], v1 = acc[ai][bj][m][1];
;             if (EPI == EPI_RES) {
;               u32x4* d = (u32x4*)(obase + (size_t)((lrow * N + lcol) * 2u));
;               const u32x4 t = *d;
;               const f32x4 r0 = bf4_to_f32(u32x2{t[0], t[1]}) + v0, r1 = bf4_to_f32(u32x2{t[2], t[3]}) + v1;
;               u32x4 w = {cvtpk(r0[0], r0[1]), cvtpk(r0[2], r0[3]), cvtpk(r1[0], r1[1]), cvtpk(r1[2], r1[3])};
;               *d = w;
;             } else {
;               const float a0 = fmaxf(v0[0], 0.f), a1 = fmaxf(v0[1], 0.f), a2 = fmaxf(v0[2], 0.f), a3 = fmaxf(v0[3], 0.f);
;               const float b0 = fmaxf(v1[0], 0.f), b1 = fmaxf(v1[1], 0.f), b2 = fmaxf(v1[2], 0.f), b3 = fmaxf(v1[3], 0.f);
;               u32x4 w = {cvtpk(a0 * a0, a1 * a1), cvtpk(a2 * a2, a3 * a3), cvtpk(b0 * b0, b1 * b1), cvtpk(b2 * b2, b3 * b3)};
;               *(u32x4*)(obase + (size_t)((lrow * N + lcol) * 2u)) = w;
;             }
;           }
;     }
;     asm volatile("s_waitcnt vmcnt(0) lgkmcnt(0)" ::: "memory");
;     __syncthreads();
	v_mul_f32_e32 v42, v47, v47
	v_cvt_pk_bf16_f32 v41, v41, v42
	v_mul_f32_e32 v42, v48, v48
	v_mul_f32_e32 v44, v49, v49
	v_cvt_pk_bf16_f32 v42, v42, v44
	v_mul_f32_e32 v44, v50, v50
	v_mul_f32_e32 v43, v43, v43
	v_cvt_pk_bf16_f32 v43, v44, v43
	v_add_u32_e32 v44, 0xa0000, v124
	v_or_b32_e32 v45, v44, v133
	v_lshlrev_b32_e32 v45, 1, v45
	v_max_f32_e32 v32, v32, v32
	global_store_dwordx4 v45, v[40:43], s[80:81] sc1
	v_max_f32_e32 v36, v36, v36
	v_max_f32_e32 v37, v37, v37
	v_max_f32_e32 v40, 0, v32
	v_max_f32_e32 v32, v33, v33
	v_max_f32_e32 v41, 0, v32
	v_max_f32_e32 v32, v34, v34
	v_max_f32_e32 v36, 0, v36
	v_max_f32_e32 v37, 0, v37
	v_max_f32_e32 v38, v38, v38
	v_max_f32_e32 v39, v39, v39
	v_max_f32_e32 v42, 0, v32
	v_max_f32_e32 v32, v35, v35
	v_max_f32_e32 v38, 0, v38
	v_max_f32_e32 v39, 0, v39
	v_max_f32_e32 v35, 0, v32
	v_mul_f32_e32 v32, v36, v36
	v_mul_f32_e32 v33, v37, v37
	v_cvt_pk_bf16_f32 v32, v32, v33
	v_mul_f32_e32 v33, v38, v38
	v_mul_f32_e32 v34, v39, v39
	v_cvt_pk_bf16_f32 v33, v33, v34
	v_mul_f32_e32 v34, v40, v40
	v_mul_f32_e32 v36, v41, v41
	v_cvt_pk_bf16_f32 v34, v34, v36
	v_mul_f32_e32 v36, v42, v42
	v_mul_f32_e32 v35, v35, v35
	v_cvt_pk_bf16_f32 v35, v36, v35
	v_add_u32_e32 v36, 0xb0000, v124
	v_or_b32_e32 v37, v36, v133
	v_lshlrev_b32_e32 v37, 1, v37
	v_max_f32_e32 v24, v24, v24
	global_store_dwordx4 v37, v[32:35], s[80:81] sc1
	v_max_f32_e32 v28, v28, v28
	v_max_f32_e32 v29, v29, v29
	v_max_f32_e32 v32, 0, v24
	v_max_f32_e32 v24, v25, v25
	v_max_f32_e32 v33, 0, v24
	v_max_f32_e32 v24, v26, v26
	v_max_f32_e32 v28, 0, v28
	v_max_f32_e32 v29, 0, v29
	v_max_f32_e32 v30, v30, v30
	v_max_f32_e32 v31, v31, v31
	v_max_f32_e32 v34, 0, v24
	v_max_f32_e32 v24, v27, v27
	v_max_f32_e32 v30, 0, v30
	v_max_f32_e32 v31, 0, v31
	v_max_f32_e32 v27, 0, v24
	v_mul_f32_e32 v24, v28, v28
	v_mul_f32_e32 v25, v29, v29
	v_cvt_pk_bf16_f32 v24, v24, v25
	v_mul_f32_e32 v25, v30, v30
	v_mul_f32_e32 v26, v31, v31
	v_cvt_pk_bf16_f32 v25, v25, v26
	v_mul_f32_e32 v26, v32, v32
	v_mul_f32_e32 v28, v33, v33
	v_cvt_pk_bf16_f32 v26, v26, v28
	v_mul_f32_e32 v28, v34, v34
	v_mul_f32_e32 v27, v27, v27
	v_cvt_pk_bf16_f32 v27, v28, v27
	v_or_b32_e32 v28, v60, v96
	v_lshlrev_b32_e32 v28, 1, v28
	v_max_f32_e32 v16, v16, v16
	global_store_dwordx4 v28, v[24:27], s[80:81] sc1
	v_max_f32_e32 v20, v20, v20
	v_max_f32_e32 v21, v21, v21
	v_max_f32_e32 v24, 0, v16
	v_max_f32_e32 v16, v17, v17
	v_max_f32_e32 v25, 0, v16
	v_max_f32_e32 v16, v18, v18
	v_max_f32_e32 v20, 0, v20
	v_max_f32_e32 v21, 0, v21
	v_max_f32_e32 v22, v22, v22
	v_max_f32_e32 v23, v23, v23
	v_max_f32_e32 v26, 0, v16
	v_max_f32_e32 v16, v19, v19
	v_max_f32_e32 v22, 0, v22
	v_max_f32_e32 v23, 0, v23
	v_max_f32_e32 v19, 0, v16
	v_mul_f32_e32 v16, v20, v20
	v_mul_f32_e32 v17, v21, v21
	v_cvt_pk_bf16_f32 v16, v16, v17
	v_mul_f32_e32 v17, v22, v22
	v_mul_f32_e32 v18, v23, v23
	v_cvt_pk_bf16_f32 v17, v17, v18
	v_mul_f32_e32 v18, v24, v24
	v_mul_f32_e32 v20, v25, v25
	v_cvt_pk_bf16_f32 v18, v18, v20
	v_mul_f32_e32 v20, v26, v26
	v_mul_f32_e32 v19, v19, v19
	v_cvt_pk_bf16_f32 v19, v20, v19
	v_or_b32_e32 v20, v52, v96
	v_lshlrev_b32_e32 v20, 1, v20
	v_max_f32_e32 v8, v8, v8
	global_store_dwordx4 v20, v[16:19], s[80:81] sc1
	v_max_f32_e32 v12, v12, v12
	v_max_f32_e32 v13, v13, v13
	v_max_f32_e32 v16, 0, v8
	v_max_f32_e32 v8, v9, v9
	v_max_f32_e32 v17, 0, v8
	v_max_f32_e32 v8, v10, v10
	v_max_f32_e32 v12, 0, v12
	v_max_f32_e32 v13, 0, v13
	v_max_f32_e32 v14, v14, v14
	v_max_f32_e32 v15, v15, v15
	v_max_f32_e32 v18, 0, v8
	v_max_f32_e32 v8, v11, v11
	v_max_f32_e32 v14, 0, v14
	v_max_f32_e32 v15, 0, v15
	v_max_f32_e32 v11, 0, v8
	v_mul_f32_e32 v8, v12, v12
	v_mul_f32_e32 v9, v13, v13
	v_cvt_pk_bf16_f32 v8, v8, v9
	v_mul_f32_e32 v9, v14, v14
	v_mul_f32_e32 v10, v15, v15
	v_cvt_pk_bf16_f32 v9, v9, v10
	v_mul_f32_e32 v10, v16, v16
	v_mul_f32_e32 v12, v17, v17
	v_cvt_pk_bf16_f32 v10, v10, v12
	v_mul_f32_e32 v12, v18, v18
	v_mul_f32_e32 v11, v11, v11
	v_cvt_pk_bf16_f32 v11, v12, v11
	v_or_b32_e32 v12, v44, v96
	v_lshlrev_b32_e32 v12, 1, v12
	v_max_f32_e32 v0, v0, v0
	global_store_dwordx4 v12, v[8:11], s[80:81] sc1
	v_max_f32_e32 v4, v4, v4
	v_max_f32_e32 v5, v5, v5
	v_max_f32_e32 v8, 0, v0
	v_max_f32_e32 v0, v1, v1
	v_max_f32_e32 v9, 0, v0
	v_max_f32_e32 v0, v2, v2
	v_max_f32_e32 v4, 0, v4
	v_max_f32_e32 v5, 0, v5
	v_max_f32_e32 v6, v6, v6
	v_max_f32_e32 v7, v7, v7
	v_max_f32_e32 v10, 0, v0
	v_max_f32_e32 v0, v3, v3
	v_max_f32_e32 v6, 0, v6
	v_max_f32_e32 v7, 0, v7
	v_max_f32_e32 v3, 0, v0
	v_mul_f32_e32 v0, v4, v4
	v_mul_f32_e32 v1, v5, v5
	v_cvt_pk_bf16_f32 v0, v0, v1
	v_mul_f32_e32 v1, v6, v6
	v_mul_f32_e32 v2, v7, v7
	v_cvt_pk_bf16_f32 v1, v1, v2
	v_mul_f32_e32 v2, v8, v8
	v_mul_f32_e32 v4, v9, v9
	v_cvt_pk_bf16_f32 v2, v2, v4
	v_mul_f32_e32 v4, v10, v10
	v_mul_f32_e32 v3, v3, v3
	v_cvt_pk_bf16_f32 v3, v4, v3
	v_or_b32_e32 v4, v36, v96
	v_lshlrev_b32_e32 v4, 1, v4
	global_store_dwordx4 v4, v[0:3], s[80:81] sc1
	s_waitcnt vmcnt(0) lgkmcnt(0)
	s_add_i32 s90, s90, s33
	s_cmpk_lt_i32 s90, 0x800
	s_waitcnt vmcnt(0)
	s_barrier
	s_cbranch_scc0 .LBB0_198

; template <int N, int K, int EPI>
; __device__ __forceinline__ void gemm_phase(const bf16* __restrict__ A, const bf16* __restrict__ Bt, float* __restrict__ outf, bf16* __restrict__ outb,
;                            const float* __restrict__ ropec, const int W) {
;     ...
;       char* obase = (char*)(outb + (size_t)brow * N + bcol);
; #pragma unroll
;       for (int ai = 0; ai < 2; ++ai)
; #pragma unroll
;         for (int bj = 0; bj < 2; ++bj)
; #pragma unroll
;           for (int m = 0; m < 4; ++m) {
;             const unsigned lrow = ai * HALF + wr * 64 + m * 16 + efr;
;             const unsigned lcol = bj * HALF + wcb + efq * 8;
;             const f32x4 v0 = acc[ai][bj][m][0], v1 = acc[ai][bj][m][1];
;             if (EPI == EPI_RES) {
;               u32x4* d = (u32x4*)(obase + (size_t)((lrow * N + lcol) * 2u));
;               const u32x4 t = *d;
;               const f32x4 r0 = bf4_to_f32(u32x2{t[0], t[1]}) + v0, r1 = bf4_to_f32(u32x2{t[2], t[3]}) + v1;
;               u32x4 w = {cvtpk(r0[0], r0[1]), cvtpk(r0[2], r0[3]), cvtpk(r1[0], r1[1]), cvtpk(r1[2], r1[3])};
;               *d = w;
;             } else {
;               const float a0 = fmaxf(v0[0], 0.f), a1 = fmaxf(v0[1], 0.f), a2 = fmaxf(v0[2], 0.f), a3 = fmaxf(v0[3], 0.f);
;               const float b0 = fmaxf(v1[0], 0.f), b1 = fmaxf(v1[1], 0.f), b2 = fmaxf(v1[2], 0.f), b3 = fmaxf(v1[3], 0.f);
;               u32x4 w = {cvtpk(a0 * a0, a1 * a1), cvtpk(a2 * a2, a3 * a3), cvtpk(b0 * b0, b1 * b1), cvtpk(b2 * b2, b3 * b3)};
;               *(u32x4*)(obase + (size_t)((lrow * N + lcol) * 2u)) = w;
;             }
.LBB0_397:
	v_max_f32_e32 v120, v120, v120
	v_max_f32_e32 v158, 0, v120
	v_max_f32_e32 v120, v121, v121
	v_max_f32_e32 v124, v124, v124
	v_max_f32_e32 v125, v125, v125
	v_max_f32_e32 v159, 0, v120
	v_max_f32_e32 v120, v122, v122
	v_max_f32_e32 v124, 0, v124
	v_max_f32_e32 v125, 0, v125
	v_max_f32_e32 v126, v126, v126
	v_max_f32_e32 v127, v127, v127
	v_max_f32_e32 v160, 0, v120
	v_max_f32_e32 v120, v123, v123
	v_max_f32_e32 v126, 0, v126
	v_max_f32_e32 v127, 0, v127
	v_max_f32_e32 v123, 0, v120
	v_mul_f32_e32 v120, v124, v124
	v_mul_f32_e32 v121, v125, v125
	v_mbcnt_lo_u32_b32 v132, -1, 0
	v_mbcnt_hi_u32_b32 v132, -1, v132
	v_cvt_pk_bf16_f32 v120, v120, v121
	v_mul_f32_e32 v121, v126, v126
	v_mul_f32_e32 v122, v127, v127
	v_cvt_pk_bf16_f32 v121, v121, v122
	v_mul_f32_e32 v122, v158, v158
	v_mul_f32_e32 v124, v159, v159
	v_cvt_pk_bf16_f32 v122, v122, v124
	v_mul_f32_e32 v124, v160, v160
	v_mul_f32_e32 v123, v123, v123
	s_lshl_b64 s[8:9], s[76:77], 13
	v_cvt_pk_bf16_f32 v123, v124, v123
	v_lshlrev_b32_e32 v124, 12, v132
	s_add_u32 s59, s36, s8
	v_lshrrev_b32_e32 v133, 1, v132
	v_and_b32_e32 v124, 0xf000, v124
	s_addc_u32 s76, s37, s9
	s_lshl_b64 s[8:9], s[74:75], 1
	v_and_or_b32 v133, v133, 24, s4
	v_or_b32_e32 v124, s5, v124
	s_add_u32 s74, s59, s8
	v_or_b32_e32 v125, v124, v133
	s_addc_u32 s75, s76, s9
	v_lshlrev_b32_e32 v125, 1, v125
	v_max_f32_e32 v112, v112, v112
	global_store_dwordx4 v125, v[120:123], s[74:75] sc1
	v_max_f32_e32 v116, v116, v116
	v_max_f32_e32 v117, v117, v117
	v_max_f32_e32 v120, 0, v112
	v_max_f32_e32 v112, v113, v113
	v_max_f32_e32 v121, 0, v112
	v_max_f32_e32 v112, v114, v114
	v_max_f32_e32 v116, 0, v116
	v_max_f32_e32 v117, 0, v117
	v_max_f32_e32 v118, v118, v118
	v_max_f32_e32 v119, v119, v119
	v_max_f32_e32 v122, 0, v112
	v_max_f32_e32 v112, v115, v115
	v_max_f32_e32 v118, 0, v118
	v_max_f32_e32 v119, 0, v119
	v_max_f32_e32 v115, 0, v112
	v_mul_f32_e32 v112, v116, v116
	v_mul_f32_e32 v113, v117, v117
	v_cvt_pk_bf16_f32 v112, v112, v113
	v_mul_f32_e32 v113, v118, v118
	v_mul_f32_e32 v114, v119, v119
	v_cvt_pk_bf16_f32 v113, v113, v114
	v_mul_f32_e32 v114, v120, v120
	v_mul_f32_e32 v116, v121, v121
	v_cvt_pk_bf16_f32 v114, v114, v116
	v_mul_f32_e32 v116, v122, v122
	v_mul_f32_e32 v115, v115, v115
	v_cvt_pk_bf16_f32 v115, v116, v115
	v_or_b32_e32 v116, 0x10000, v124
	v_or_b32_e32 v117, v116, v133
	v_lshlrev_b32_e32 v117, 1, v117
	v_max_f32_e32 v104, v104, v104
	global_store_dwordx4 v117, v[112:115], s[74:75] sc1
	v_max_f32_e32 v108, v108, v108
	v_max_f32_e32 v109, v109, v109
	v_max_f32_e32 v112, 0, v104
	v_max_f32_e32 v104, v105, v105
	v_max_f32_e32 v113, 0, v104
	v_max_f32_e32 v104, v106, v106
	v_max_f32_e32 v108, 0, v108
	v_max_f32_e32 v109, 0, v109
	v_max_f32_e32 v110, v110, v110
	v_max_f32_e32 v111, v111, v111
	v_max_f32_e32 v114, 0, v104
	v_max_f32_e32 v104, v107, v107
	v_max_f32_e32 v110, 0, v110
	v_max_f32_e32 v111, 0, v111
	v_max_f32_e32 v107, 0, v104
	v_mul_f32_e32 v104, v108, v108
	v_mul_f32_e32 v105, v109, v109
	v_cvt_pk_bf16_f32 v104, v104, v105
	v_mul_f32_e32 v105, v110, v110
	v_mul_f32_e32 v106, v111, v111
	v_cvt_pk_bf16_f32 v105, v105, v106
	v_mul_f32_e32 v106, v112, v112
	v_mul_f32_e32 v108, v113, v113
	v_cvt_pk_bf16_f32 v106, v106, v108
	v_mul_f32_e32 v108, v114, v114
	v_mul_f32_e32 v107, v107, v107
	v_cvt_pk_bf16_f32 v107, v108, v107
	v_or_b32_e32 v108, 0x20000, v124
	v_or_b32_e32 v109, v108, v133
	v_lshlrev_b32_e32 v109, 1, v109
	v_max_f32_e32 v96, v96, v96
	global_store_dwordx4 v109, v[104:107], s[74:75] sc1
	v_max_f32_e32 v100, v100, v100
	v_max_f32_e32 v101, v101, v101
	v_max_f32_e32 v104, 0, v96
	v_max_f32_e32 v96, v97, v97
	v_max_f32_e32 v105, 0, v96
	v_max_f32_e32 v96, v98, v98
	v_max_f32_e32 v100, 0, v100
	v_max_f32_e32 v101, 0, v101
	v_max_f32_e32 v102, v102, v102
	v_max_f32_e32 v103, v103, v103
	v_max_f32_e32 v106, 0, v96
	v_max_f32_e32 v96, v99, v99
	v_max_f32_e32 v102, 0, v102
	v_max_f32_e32 v103, 0, v103
	v_max_f32_e32 v99, 0, v96
	v_mul_f32_e32 v96, v100, v100
	v_mul_f32_e32 v97, v101, v101
	v_cvt_pk_bf16_f32 v96, v96, v97
	v_mul_f32_e32 v97, v102, v102
	v_mul_f32_e32 v98, v103, v103
	v_cvt_pk_bf16_f32 v97, v97, v98
	v_mul_f32_e32 v98, v104, v104
	v_mul_f32_e32 v100, v105, v105
	v_cvt_pk_bf16_f32 v98, v98, v100
	v_mul_f32_e32 v100, v106, v106
	v_mul_f32_e32 v99, v99, v99
	v_cvt_pk_bf16_f32 v99, v100, v99
	v_or_b32_e32 v100, 0x30000, v124
	v_or_b32_e32 v101, v100, v133
	v_lshlrev_b32_e32 v101, 1, v101
	v_max_f32_e32 v88, v88, v88
	global_store_dwordx4 v101, v[96:99], s[74:75] sc1
	v_max_f32_e32 v92, v92, v92
	v_max_f32_e32 v93, v93, v93
	v_max_f32_e32 v97, 0, v88
	v_max_f32_e32 v88, v89, v89
	v_max_f32_e32 v98, 0, v88
	v_max_f32_e32 v88, v90, v90
	v_max_f32_e32 v92, 0, v92
	v_max_f32_e32 v93, 0, v93
	v_max_f32_e32 v94, v94, v94
	v_max_f32_e32 v95, v95, v95
	v_max_f32_e32 v99, 0, v88
	v_max_f32_e32 v88, v91, v91
	v_max_f32_e32 v94, 0, v94
	v_max_f32_e32 v95, 0, v95
	v_max_f32_e32 v91, 0, v88
	v_mul_f32_e32 v88, v92, v92
	v_mul_f32_e32 v89, v93, v93
	v_cvt_pk_bf16_f32 v88, v88, v89
	v_mul_f32_e32 v89, v94, v94
	v_mul_f32_e32 v90, v95, v95
	v_cvt_pk_bf16_f32 v89, v89, v90
	v_mul_f32_e32 v90, v97, v97
	v_mul_f32_e32 v92, v98, v98
	v_or_b32_e32 v96, 0x80, v133
	v_cvt_pk_bf16_f32 v90, v90, v92
	v_mul_f32_e32 v92, v99, v99
	v_mul_f32_e32 v91, v91, v91
	v_cvt_pk_bf16_f32 v91, v92, v91
	v_or_b32_e32 v92, v96, v124
	v_lshlrev_b32_e32 v92, 1, v92
	v_max_f32_e32 v80, v80, v80
	global_store_dwordx4 v92, v[88:91], s[74:75] sc1
	v_max_f32_e32 v84, v84, v84
	v_max_f32_e32 v85, v85, v85
	v_max_f32_e32 v88, 0, v80
	v_max_f32_e32 v80, v81, v81
	v_max_f32_e32 v89, 0, v80
	v_max_f32_e32 v80, v82, v82
; template <int N, int K, int EPI>
; __device__ __forceinline__ void gemm_phase(const bf16* __restrict__ A, const bf16* __restrict__ Bt, float* __restrict__ outf, bf16* __restrict__ outb,
;                            const float* __restrict__ ropec, const int W) {
;     ...
;       char* obase = (char*)(outb + (size_t)brow * N + bcol);
; #pragma unroll
;       for (int ai = 0; ai < 2; ++ai)
; #pragma unroll
;         for (int bj = 0; bj < 2; ++bj)
; #pragma unroll
;           for (int m = 0; m < 4; ++m) {
;             const unsigned lrow = ai * HALF + wr * 64 + m * 16 + efr;
;             const unsigned lcol = bj * HALF + wcb + efq * 8;
;             const f32x4 v0 = acc[ai][bj][m][0], v1 = acc[ai][bj][m][1];
;             if (EPI == EPI_RES) {
;               u32x4* d = (u32x4*)(obase + (size_t)((lrow * N + lcol) * 2u));
;               const u32x4 t = *d;
;               const f32x4 r0 = bf4_to_f32(u32x2{t[0], t[1]}) + v0, r1 = bf4_to_f32(u32x2{t[2], t[3]}) + v1;
;               u32x4 w = {cvtpk(r0[0], r0[1]), cvtpk(r0[2], r0[3]), cvtpk(r1[0], r1[1]), cvtpk(r1[2], r1[3])};
;               *d = w;
;             } else {
;               const float a0 = fmaxf(v0[0], 0.f), a1 = fmaxf(v0[1], 0.f), a2 = fmaxf(v0[2], 0.f), a3 = fmaxf(v0[3], 0.f);
;               const float b0 = fmaxf(v1[0], 0.f), b1 = fmaxf(v1[1], 0.f), b2 = fmaxf(v1[2], 0.f), b3 = fmaxf(v1[3], 0.f);
;               u32x4 w = {cvtpk(a0 * a0, a1 * a1), cvtpk(a2 * a2, a3 * a3), cvtpk(b0 * b0, b1 * b1), cvtpk(b2 * b2, b3 * b3)};
;               *(u32x4*)(obase + (size_t)((lrow * N + lcol) * 2u)) = w;
;             }
	v_max_f32_e32 v84, 0, v84
	v_max_f32_e32 v85, 0, v85
	v_max_f32_e32 v86, v86, v86
	v_max_f32_e32 v87, v87, v87
	v_max_f32_e32 v90, 0, v80
	v_max_f32_e32 v80, v83, v83
	v_max_f32_e32 v86, 0, v86
	v_max_f32_e32 v87, 0, v87
	v_max_f32_e32 v83, 0, v80
	v_mul_f32_e32 v80, v84, v84
	v_mul_f32_e32 v81, v85, v85
	v_cvt_pk_bf16_f32 v80, v80, v81
	v_mul_f32_e32 v81, v86, v86
	v_mul_f32_e32 v82, v87, v87
	v_cvt_pk_bf16_f32 v81, v81, v82
	v_mul_f32_e32 v82, v88, v88
	v_mul_f32_e32 v84, v89, v89
	v_cvt_pk_bf16_f32 v82, v82, v84
	v_mul_f32_e32 v84, v90, v90
	v_mul_f32_e32 v83, v83, v83
	v_cvt_pk_bf16_f32 v83, v84, v83
	v_or_b32_e32 v84, v116, v96
	v_lshlrev_b32_e32 v84, 1, v84
	v_max_f32_e32 v72, v72, v72
	global_store_dwordx4 v84, v[80:83], s[74:75] sc1
	v_max_f32_e32 v76, v76, v76
	v_max_f32_e32 v77, v77, v77
	v_max_f32_e32 v80, 0, v72
	v_max_f32_e32 v72, v73, v73
	v_max_f32_e32 v81, 0, v72
	v_max_f32_e32 v72, v74, v74
	v_max_f32_e32 v76, 0, v76
	v_max_f32_e32 v77, 0, v77
	v_max_f32_e32 v78, v78, v78
	v_max_f32_e32 v79, v79, v79
	v_max_f32_e32 v82, 0, v72
	v_max_f32_e32 v72, v75, v75
	v_max_f32_e32 v78, 0, v78
	v_max_f32_e32 v79, 0, v79
	v_max_f32_e32 v75, 0, v72
	v_mul_f32_e32 v72, v76, v76
	v_mul_f32_e32 v73, v77, v77
	v_cvt_pk_bf16_f32 v72, v72, v73
	v_mul_f32_e32 v73, v78, v78
	v_mul_f32_e32 v74, v79, v79
	v_cvt_pk_bf16_f32 v73, v73, v74
	v_mul_f32_e32 v74, v80, v80
	v_mul_f32_e32 v76, v81, v81
	v_cvt_pk_bf16_f32 v74, v74, v76
	v_mul_f32_e32 v76, v82, v82
	v_mul_f32_e32 v75, v75, v75
	v_cvt_pk_bf16_f32 v75, v76, v75
	v_or_b32_e32 v76, v108, v96
	v_lshlrev_b32_e32 v76, 1, v76
	v_max_f32_e32 v64, v64, v64
	global_store_dwordx4 v76, v[72:75], s[74:75] sc1
	v_max_f32_e32 v68, v68, v68
	v_max_f32_e32 v69, v69, v69
	v_max_f32_e32 v72, 0, v64
	v_max_f32_e32 v64, v65, v65
	v_max_f32_e32 v73, 0, v64
	v_max_f32_e32 v64, v66, v66
	v_max_f32_e32 v68, 0, v68
	v_max_f32_e32 v69, 0, v69
	v_max_f32_e32 v70, v70, v70
	v_max_f32_e32 v71, v71, v71
	v_max_f32_e32 v74, 0, v64
	v_max_f32_e32 v64, v67, v67
	v_max_f32_e32 v70, 0, v70
	v_max_f32_e32 v71, 0, v71
	v_max_f32_e32 v67, 0, v64
	v_mul_f32_e32 v64, v68, v68
	v_mul_f32_e32 v65, v69, v69
	v_cvt_pk_bf16_f32 v64, v64, v65
	v_mul_f32_e32 v65, v70, v70
	v_mul_f32_e32 v66, v71, v71
	v_cvt_pk_bf16_f32 v65, v65, v66
	v_mul_f32_e32 v66, v72, v72
	v_mul_f32_e32 v68, v73, v73
	v_cvt_pk_bf16_f32 v66, v66, v68
	v_mul_f32_e32 v68, v74, v74
	v_mul_f32_e32 v67, v67, v67
	v_cvt_pk_bf16_f32 v67, v68, v67
	v_or_b32_e32 v68, v100, v96
	v_lshlrev_b32_e32 v68, 1, v68
	v_max_f32_e32 v56, v56, v56
	global_store_dwordx4 v68, v[64:67], s[74:75] sc1
	v_max_f32_e32 v60, v60, v60
	v_max_f32_e32 v61, v61, v61
	v_max_f32_e32 v64, 0, v56
	v_max_f32_e32 v56, v57, v57
	v_max_f32_e32 v65, 0, v56
	v_max_f32_e32 v56, v58, v58
	v_max_f32_e32 v60, 0, v60
	v_max_f32_e32 v61, 0, v61
	v_max_f32_e32 v62, v62, v62
	v_max_f32_e32 v63, v63, v63
	v_max_f32_e32 v66, 0, v56
	v_max_f32_e32 v56, v59, v59
	v_max_f32_e32 v62, 0, v62
	v_max_f32_e32 v63, 0, v63
	v_max_f32_e32 v59, 0, v56
	v_mul_f32_e32 v56, v60, v60
	v_mul_f32_e32 v57, v61, v61
	v_cvt_pk_bf16_f32 v56, v56, v57
	v_mul_f32_e32 v57, v62, v62
	v_mul_f32_e32 v58, v63, v63
	v_cvt_pk_bf16_f32 v57, v57, v58
	v_mul_f32_e32 v58, v64, v64
	v_mul_f32_e32 v60, v65, v65
	v_cvt_pk_bf16_f32 v58, v58, v60
	v_mul_f32_e32 v60, v66, v66
	v_mul_f32_e32 v59, v59, v59
	v_cvt_pk_bf16_f32 v59, v60, v59
	v_add_u32_e32 v60, 0x80000, v124
	v_or_b32_e32 v61, v60, v133
	v_lshlrev_b32_e32 v61, 1, v61
	v_max_f32_e32 v48, v48, v48
	global_store_dwordx4 v61, v[56:59], s[74:75] sc1
	v_max_f32_e32 v52, v52, v52
	v_max_f32_e32 v53, v53, v53
	v_max_f32_e32 v56, 0, v48
	v_max_f32_e32 v48, v49, v49
	v_max_f32_e32 v57, 0, v48
	v_max_f32_e32 v48, v50, v50
	v_max_f32_e32 v52, 0, v52
	v_max_f32_e32 v53, 0, v53
	v_max_f32_e32 v54, v54, v54
	v_max_f32_e32 v55, v55, v55
	v_max_f32_e32 v58, 0, v48
	v_max_f32_e32 v48, v51, v51
	v_max_f32_e32 v54, 0, v54
	v_max_f32_e32 v55, 0, v55
	v_max_f32_e32 v51, 0, v48
	v_mul_f32_e32 v48, v52, v52
	v_mul_f32_e32 v49, v53, v53
	v_cvt_pk_bf16_f32 v48, v48, v49
	v_mul_f32_e32 v49, v54, v54
	v_mul_f32_e32 v50, v55, v55
	v_cvt_pk_bf16_f32 v49, v49, v50
	v_mul_f32_e32 v50, v56, v56
	v_mul_f32_e32 v52, v57, v57
	v_cvt_pk_bf16_f32 v50, v50, v52
	v_mul_f32_e32 v52, v58, v58
	v_mul_f32_e32 v51, v51, v51
	v_cvt_pk_bf16_f32 v51, v52, v51
	v_add_u32_e32 v52, 0x90000, v124
	v_or_b32_e32 v53, v52, v133
	v_lshlrev_b32_e32 v53, 1, v53
	v_max_f32_e32 v40, v40, v40
	global_store_dwordx4 v53, v[48:51], s[74:75] sc1
	v_max_f32_e32 v44, v44, v44
	v_max_f32_e32 v45, v45, v45
	v_max_f32_e32 v48, 0, v40
	v_max_f32_e32 v40, v41, v41
	v_max_f32_e32 v49, 0, v40
	v_max_f32_e32 v40, v42, v42
	v_max_f32_e32 v44, 0, v44
	v_max_f32_e32 v45, 0, v45
	v_max_f32_e32 v46, v46, v46
	v_max_f32_e32 v47, v47, v47
	v_max_f32_e32 v50, 0, v40
	v_max_f32_e32 v40, v43, v43
	v_max_f32_e32 v46, 0, v46
	v_max_f32_e32 v47, 0, v47
	v_max_f32_e32 v43, 0, v40
	v_mul_f32_e32 v40, v44, v44
	v_mul_f32_e32 v41, v45, v45
	v_cvt_pk_bf16_f32 v40, v40, v41
	v_mul_f32_e32 v41, v46, v46
; template <int N, int K, int EPI>
; __device__ __forceinline__ void gemm_phase(const bf16* __restrict__ A, const bf16* __restrict__ Bt, float* __restrict__ outf, bf16* __restrict__ outb,
;                            const float* __restrict__ ropec, const int W) {
;     ...
;       char* obase = (char*)(outb + (size_t)brow * N + bcol);
; #pragma unroll
;       for (int ai = 0; ai < 2; ++ai)
; #pragma unroll
;         for (int bj = 0; bj < 2; ++bj)
; #pragma unroll
;           for (int m = 0; m < 4; ++m) {
;             const unsigned lrow = ai * HALF + wr * 64 + m * 16 + efr;
;             const unsigned lcol = bj * HALF + wcb + efq * 8;
;             const f32x4 v0 = acc[ai][bj][m][0], v1 = acc[ai][bj][m][1];
;             if (EPI == EPI_RES) {
;               u32x4* d = (u32x4*)(obase + (size_t)((lrow * N + lcol) * 2u));
;               const u32x4 t = *d;
;               const f32x4 r0 = bf4_to_f32(u32x2{t[0], t[1]}) + v0, r1 = bf4_to_f32(u32x2{t[2], t[3]}) + v1;
;               u32x4 w = {cvtpk(r0[0], r0[1]), cvtpk(r0[2], r0[3]), cvtpk(r1[0], r1[1]), cvtpk(r1[2], r1[3])};
;               *d = w;
;             } else {
;               const float a0 = fmaxf(v0[0], 0.f), a1 = fmaxf(v0[1], 0.f), a2 = fmaxf(v0[2], 0.f), a3 = fmaxf(v0[3], 0.f);
;               const float b0 = fmaxf(v1[0], 0.f), b1 = fmaxf(v1[1], 0.f), b2 = fmaxf(v1[2], 0.f), b3 = fmaxf(v1[3], 0.f);
;               u32x4 w = {cvtpk(a0 * a0, a1 * a1), cvtpk(a2 * a2, a3 * a3), cvtpk(b0 * b0, b1 * b1), cvtpk(b2 * b2, b3 * b3)};
;               *(u32x4*)(obase + (size_t)((lrow * N + lcol) * 2u)) = w;
;             }
;           }
;     }
;     asm volatile("s_waitcnt vmcnt(0) lgkmcnt(0)" ::: "memory");
;     __syncthreads();
	v_mul_f32_e32 v42, v47, v47
	v_cvt_pk_bf16_f32 v41, v41, v42
	v_mul_f32_e32 v42, v48, v48
	v_mul_f32_e32 v44, v49, v49
	v_cvt_pk_bf16_f32 v42, v42, v44
	v_mul_f32_e32 v44, v50, v50
	v_mul_f32_e32 v43, v43, v43
	v_cvt_pk_bf16_f32 v43, v44, v43
	v_add_u32_e32 v44, 0xa0000, v124
	v_or_b32_e32 v45, v44, v133
	v_lshlrev_b32_e32 v45, 1, v45
	v_max_f32_e32 v32, v32, v32
	global_store_dwordx4 v45, v[40:43], s[74:75] sc1
	v_max_f32_e32 v36, v36, v36
	v_max_f32_e32 v37, v37, v37
	v_max_f32_e32 v40, 0, v32
	v_max_f32_e32 v32, v33, v33
	v_max_f32_e32 v41, 0, v32
	v_max_f32_e32 v32, v34, v34
	v_max_f32_e32 v36, 0, v36
	v_max_f32_e32 v37, 0, v37
	v_max_f32_e32 v38, v38, v38
	v_max_f32_e32 v39, v39, v39
	v_max_f32_e32 v42, 0, v32
	v_max_f32_e32 v32, v35, v35
	v_max_f32_e32 v38, 0, v38
	v_max_f32_e32 v39, 0, v39
	v_max_f32_e32 v35, 0, v32
	v_mul_f32_e32 v32, v36, v36
	v_mul_f32_e32 v33, v37, v37
	v_cvt_pk_bf16_f32 v32, v32, v33
	v_mul_f32_e32 v33, v38, v38
	v_mul_f32_e32 v34, v39, v39
	v_cvt_pk_bf16_f32 v33, v33, v34
	v_mul_f32_e32 v34, v40, v40
	v_mul_f32_e32 v36, v41, v41
	v_cvt_pk_bf16_f32 v34, v34, v36
	v_mul_f32_e32 v36, v42, v42
	v_mul_f32_e32 v35, v35, v35
	v_cvt_pk_bf16_f32 v35, v36, v35
	v_add_u32_e32 v36, 0xb0000, v124
	v_or_b32_e32 v37, v36, v133
	v_lshlrev_b32_e32 v37, 1, v37
	v_max_f32_e32 v24, v24, v24
	global_store_dwordx4 v37, v[32:35], s[74:75] sc1
	v_max_f32_e32 v28, v28, v28
	v_max_f32_e32 v29, v29, v29
	v_max_f32_e32 v32, 0, v24
	v_max_f32_e32 v24, v25, v25
	v_max_f32_e32 v33, 0, v24
	v_max_f32_e32 v24, v26, v26
	v_max_f32_e32 v28, 0, v28
	v_max_f32_e32 v29, 0, v29
	v_max_f32_e32 v30, v30, v30
	v_max_f32_e32 v31, v31, v31
	v_max_f32_e32 v34, 0, v24
	v_max_f32_e32 v24, v27, v27
	v_max_f32_e32 v30, 0, v30
	v_max_f32_e32 v31, 0, v31
	v_max_f32_e32 v27, 0, v24
	v_mul_f32_e32 v24, v28, v28
	v_mul_f32_e32 v25, v29, v29
	v_cvt_pk_bf16_f32 v24, v24, v25
	v_mul_f32_e32 v25, v30, v30
	v_mul_f32_e32 v26, v31, v31
	v_cvt_pk_bf16_f32 v25, v25, v26
	v_mul_f32_e32 v26, v32, v32
	v_mul_f32_e32 v28, v33, v33
	v_cvt_pk_bf16_f32 v26, v26, v28
	v_mul_f32_e32 v28, v34, v34
	v_mul_f32_e32 v27, v27, v27
	v_cvt_pk_bf16_f32 v27, v28, v27
	v_or_b32_e32 v28, v60, v96
	v_lshlrev_b32_e32 v28, 1, v28
	v_max_f32_e32 v16, v16, v16
	global_store_dwordx4 v28, v[24:27], s[74:75] sc1
	v_max_f32_e32 v20, v20, v20
	v_max_f32_e32 v21, v21, v21
	v_max_f32_e32 v24, 0, v16
	v_max_f32_e32 v16, v17, v17
	v_max_f32_e32 v25, 0, v16
	v_max_f32_e32 v16, v18, v18
	v_max_f32_e32 v20, 0, v20
	v_max_f32_e32 v21, 0, v21
	v_max_f32_e32 v22, v22, v22
	v_max_f32_e32 v23, v23, v23
	v_max_f32_e32 v26, 0, v16
	v_max_f32_e32 v16, v19, v19
	v_max_f32_e32 v22, 0, v22
	v_max_f32_e32 v23, 0, v23
	v_max_f32_e32 v19, 0, v16
	v_mul_f32_e32 v16, v20, v20
	v_mul_f32_e32 v17, v21, v21
	v_cvt_pk_bf16_f32 v16, v16, v17
	v_mul_f32_e32 v17, v22, v22
	v_mul_f32_e32 v18, v23, v23
	v_cvt_pk_bf16_f32 v17, v17, v18
	v_mul_f32_e32 v18, v24, v24
	v_mul_f32_e32 v20, v25, v25
	v_cvt_pk_bf16_f32 v18, v18, v20
	v_mul_f32_e32 v20, v26, v26
	v_mul_f32_e32 v19, v19, v19
	v_cvt_pk_bf16_f32 v19, v20, v19
	v_or_b32_e32 v20, v52, v96
	v_lshlrev_b32_e32 v20, 1, v20
	v_max_f32_e32 v8, v8, v8
	global_store_dwordx4 v20, v[16:19], s[74:75] sc1
	v_max_f32_e32 v12, v12, v12
	v_max_f32_e32 v13, v13, v13
	v_max_f32_e32 v16, 0, v8
	v_max_f32_e32 v8, v9, v9
	v_max_f32_e32 v17, 0, v8
	v_max_f32_e32 v8, v10, v10
	v_max_f32_e32 v12, 0, v12
	v_max_f32_e32 v13, 0, v13
	v_max_f32_e32 v14, v14, v14
	v_max_f32_e32 v15, v15, v15
	v_max_f32_e32 v18, 0, v8
	v_max_f32_e32 v8, v11, v11
	v_max_f32_e32 v14, 0, v14
	v_max_f32_e32 v15, 0, v15
	v_max_f32_e32 v11, 0, v8
	v_mul_f32_e32 v8, v12, v12
	v_mul_f32_e32 v9, v13, v13
	v_cvt_pk_bf16_f32 v8, v8, v9
	v_mul_f32_e32 v9, v14, v14
	v_mul_f32_e32 v10, v15, v15
	v_cvt_pk_bf16_f32 v9, v9, v10
	v_mul_f32_e32 v10, v16, v16
	v_mul_f32_e32 v12, v17, v17
	v_cvt_pk_bf16_f32 v10, v10, v12
	v_mul_f32_e32 v12, v18, v18
	v_mul_f32_e32 v11, v11, v11
	v_cvt_pk_bf16_f32 v11, v12, v11
	v_or_b32_e32 v12, v44, v96
	v_lshlrev_b32_e32 v12, 1, v12
	v_max_f32_e32 v0, v0, v0
	global_store_dwordx4 v12, v[8:11], s[74:75] sc1
	v_max_f32_e32 v4, v4, v4
	v_max_f32_e32 v5, v5, v5
	v_max_f32_e32 v8, 0, v0
	v_max_f32_e32 v0, v1, v1
	v_max_f32_e32 v9, 0, v0
	v_max_f32_e32 v0, v2, v2
	v_max_f32_e32 v4, 0, v4
	v_max_f32_e32 v5, 0, v5
	v_max_f32_e32 v6, v6, v6
	v_max_f32_e32 v7, v7, v7
	v_max_f32_e32 v10, 0, v0
	v_max_f32_e32 v0, v3, v3
	v_max_f32_e32 v6, 0, v6
	v_max_f32_e32 v7, 0, v7
	v_max_f32_e32 v3, 0, v0
	v_mul_f32_e32 v0, v4, v4
	v_mul_f32_e32 v1, v5, v5
	v_cvt_pk_bf16_f32 v0, v0, v1
	v_mul_f32_e32 v1, v6, v6
	v_mul_f32_e32 v2, v7, v7
	v_cvt_pk_bf16_f32 v1, v1, v2
	v_mul_f32_e32 v2, v8, v8
	v_mul_f32_e32 v4, v9, v9
	v_cvt_pk_bf16_f32 v2, v2, v4
	v_mul_f32_e32 v4, v10, v10
	v_mul_f32_e32 v3, v3, v3
	v_cvt_pk_bf16_f32 v3, v4, v3
	v_or_b32_e32 v4, v36, v96
	v_lshlrev_b32_e32 v4, 1, v4
	global_store_dwordx4 v4, v[0:3], s[74:75] sc1
	s_waitcnt vmcnt(0) lgkmcnt(0)
	s_add_i32 s55, s55, s33
	s_cmpk_lt_i32 s55, 0x800
	s_waitcnt vmcnt(0)
	s_barrier
	s_cbranch_scc0 .LBB0_408
